# attention unit epilogue: exact vmcnt for the 3rd/4th gate-row load (compiler's count ignored the inline-asm write-through stores)
# speedup vs baseline: 1.0343x; 1.0012x over previous
.LBB0_1417:
	v_cmp_gt_u32_e32 vcc, 32, v188
	s_and_saveexec_b64 s[2:3], vcc
	v_lshl_add_u32 v44, v188, 2, s97
	ds_write_b32 v44, v43 offset:128
	s_or_b64 exec, exec, s[2:3]
	s_waitcnt lgkmcnt(0)
	ds_read_b128 v[44:47], v196 offset:128
	v_mov_b32_e32 v48, v80
	v_mov_b32_e32 v49, v96
	v_lshlrev_b32_e32 v43, 1, v193
	v_mov_b32_e32 v96, v81
	s_waitcnt lgkmcnt(0)
	v_rcp_f32_e32 v44, v44
	s_waitcnt vmcnt(3)
	v_lshlrev_b32_e32 v50, 16, v36
	v_and_b32_e32 v51, 0xffff0000, v36
	v_lshl_add_u64 v[40:41], s[30:31], 0, v[40:41]
	v_pk_mul_f32 v[48:49], v[48:49], v[44:45] op_sel_hi:[1,0]
	v_lshl_add_u64 v[40:41], v[40:41], 0, s[6:7]
	v_cvt_pk_bf16_f32 v44, v48, v49
	v_lshlrev_b32_e32 v48, 9, v192
	v_add3_u32 v43, s74, v43, v48
	ds_write_b16 v43, v44
	ds_write_b16_d16_hi v43, v44 offset:64
	v_rcp_f32_e32 v44, v45
	v_mov_b32_e32 v48, v82
	v_mov_b32_e32 v49, v98
	v_mov_b32_e32 v98, v83
	v_pk_mul_f32 v[44:45], v[96:97], v[44:45] op_sel_hi:[1,0]
	v_lshl_add_u64 v[40:41], v[40:41], 0, v[112:113]
	v_cvt_pk_bf16_f32 v44, v44, v45
	ds_write_b16 v43, v44 offset:128
	ds_write_b16_d16_hi v43, v44 offset:192
	v_rcp_f32_e32 v44, v46
	s_andn2_b64 vcc, exec, s[60:61]
	s_mov_b64 s[34:35], 0
	v_pk_mul_f32 v[44:45], v[48:49], v[44:45] op_sel_hi:[1,0]
	s_nop 0
	v_cvt_pk_bf16_f32 v44, v44, v45
	ds_write_b16 v43, v44 offset:256
	ds_write_b16_d16_hi v43, v44 offset:320
	v_rcp_f32_e32 v44, v47
	v_mov_b32_e32 v48, v84
	v_mov_b32_e32 v49, v100
	v_mov_b32_e32 v100, v85
	v_pk_mul_f32 v[44:45], v[98:99], v[44:45] op_sel_hi:[1,0]
	s_nop 0
	v_cvt_pk_bf16_f32 v44, v44, v45
	ds_write_b16 v43, v44 offset:384
	ds_write_b16_d16_hi v43, v44 offset:448
	ds_read_b128 v[44:47], v196 offset:160
	s_waitcnt lgkmcnt(0)
	v_rcp_f32_e32 v44, v44
	s_nop 0
	v_pk_mul_f32 v[48:49], v[48:49], v[44:45] op_sel_hi:[1,0]
	s_nop 0
	v_cvt_pk_bf16_f32 v44, v48, v49
	ds_write_b16 v43, v44 offset:1024
	ds_write_b16_d16_hi v43, v44 offset:1088
	v_rcp_f32_e32 v44, v45
	v_mov_b32_e32 v48, v86
	v_mov_b32_e32 v49, v102
	v_mov_b32_e32 v102, v87
	v_pk_mul_f32 v[44:45], v[100:101], v[44:45] op_sel_hi:[1,0]
	s_nop 0
	v_cvt_pk_bf16_f32 v44, v44, v45
	ds_write_b16 v43, v44 offset:1152
	ds_write_b16_d16_hi v43, v44 offset:1216
	v_rcp_f32_e32 v44, v46
	s_nop 0
	v_pk_mul_f32 v[44:45], v[48:49], v[44:45] op_sel_hi:[1,0]
	s_nop 0
	v_cvt_pk_bf16_f32 v44, v44, v45
	ds_write_b16 v43, v44 offset:1280
	ds_write_b16_d16_hi v43, v44 offset:1344
	v_rcp_f32_e32 v44, v47
	v_mov_b32_e32 v48, v88
	v_mov_b32_e32 v49, v104
	v_mov_b32_e32 v104, v89
	v_pk_mul_f32 v[44:45], v[102:103], v[44:45] op_sel_hi:[1,0]
	s_nop 0
	v_cvt_pk_bf16_f32 v44, v44, v45
	ds_write_b16 v43, v44 offset:1408
	ds_write_b16_d16_hi v43, v44 offset:1472
	ds_read_b128 v[44:47], v196 offset:192
	s_waitcnt lgkmcnt(0)
	v_rcp_f32_e32 v44, v44
	s_nop 0
	v_pk_mul_f32 v[48:49], v[48:49], v[44:45] op_sel_hi:[1,0]
	s_nop 0
	v_cvt_pk_bf16_f32 v44, v48, v49
	ds_write_b16 v43, v44 offset:2048
	ds_write_b16_d16_hi v43, v44 offset:2112
	v_rcp_f32_e32 v44, v45
	v_mov_b32_e32 v48, v90
	v_mov_b32_e32 v49, v106
	v_mov_b32_e32 v106, v91
	v_pk_mul_f32 v[44:45], v[104:105], v[44:45] op_sel_hi:[1,0]
	s_nop 0
	v_cvt_pk_bf16_f32 v44, v44, v45
	ds_write_b16 v43, v44 offset:2176
	ds_write_b16_d16_hi v43, v44 offset:2240
	v_rcp_f32_e32 v44, v46
	s_nop 0
	v_pk_mul_f32 v[44:45], v[48:49], v[44:45] op_sel_hi:[1,0]
	s_nop 0
	v_cvt_pk_bf16_f32 v44, v44, v45
	ds_write_b16 v43, v44 offset:2304
	ds_write_b16_d16_hi v43, v44 offset:2368
	v_rcp_f32_e32 v44, v47
	v_mov_b32_e32 v48, v92
	v_mov_b32_e32 v49, v108
	v_mov_b32_e32 v108, v93
	v_pk_mul_f32 v[44:45], v[106:107], v[44:45] op_sel_hi:[1,0]
	s_nop 0
	v_cvt_pk_bf16_f32 v44, v44, v45
	ds_write_b16 v43, v44 offset:2432
	ds_write_b16_d16_hi v43, v44 offset:2496
	ds_read_b128 v[44:47], v196 offset:224
	s_waitcnt lgkmcnt(0)
	v_rcp_f32_e32 v44, v44
	s_nop 0
	v_pk_mul_f32 v[48:49], v[48:49], v[44:45] op_sel_hi:[1,0]
	s_nop 0
	v_cvt_pk_bf16_f32 v44, v48, v49
	ds_write_b16 v43, v44 offset:3072
	ds_write_b16_d16_hi v43, v44 offset:3136
	v_rcp_f32_e32 v44, v45
	v_mov_b32_e32 v48, v94
	v_mov_b32_e32 v49, v110
	v_mov_b32_e32 v110, v95
	v_pk_mul_f32 v[44:45], v[108:109], v[44:45] op_sel_hi:[1,0]
	s_nop 0
	v_cvt_pk_bf16_f32 v44, v44, v45
	ds_write_b16 v43, v44 offset:3200
	ds_write_b16_d16_hi v43, v44 offset:3264
	v_rcp_f32_e32 v44, v46
	s_nop 0
	v_pk_mul_f32 v[44:45], v[48:49], v[44:45] op_sel_hi:[1,0]
	s_nop 0
	v_cvt_pk_bf16_f32 v44, v44, v45
	ds_write_b16 v43, v44 offset:3328
	ds_write_b16_d16_hi v43, v44 offset:3392
	v_rcp_f32_e32 v44, v47
	s_nop 0
	v_pk_mul_f32 v[44:45], v[110:111], v[44:45] op_sel_hi:[1,0]
	s_nop 0
	v_cvt_pk_bf16_f32 v44, v44, v45
	ds_write_b16 v43, v44 offset:3456
	ds_write_b16_d16_hi v43, v44 offset:3520
	v_add_u32_e32 v43, s74, v112
	s_waitcnt lgkmcnt(0)
	v_lshl_add_u32 v44, v42, 7, v43
	ds_read_b128 v[44:47], v44
	s_waitcnt lgkmcnt(0)
	v_lshlrev_b32_e32 v48, 16, v44
	v_and_b32_e32 v49, 0xffff0000, v44
	v_pk_mul_f32 v[48:49], v[50:51], v[48:49]
	v_lshlrev_b32_e32 v44, 16, v45
	v_cvt_pk_bf16_f32 v36, v48, v49
	v_and_b32_e32 v45, 0xffff0000, v45
	v_lshlrev_b32_e32 v48, 16, v37
	v_and_b32_e32 v49, 0xffff0000, v37
	v_pk_mul_f32 v[44:45], v[48:49], v[44:45]
	v_lshlrev_b32_e32 v48, 16, v38
	v_cvt_pk_bf16_f32 v37, v44, v45
	v_lshlrev_b32_e32 v44, 16, v46
	v_and_b32_e32 v45, 0xffff0000, v46
	v_and_b32_e32 v49, 0xffff0000, v38
	v_pk_mul_f32 v[44:45], v[48:49], v[44:45]
	v_lshlrev_b32_e32 v46, 16, v39
	v_cvt_pk_bf16_f32 v38, v44, v45
	v_lshlrev_b32_e32 v44, 16, v47
	v_and_b32_e32 v45, 0xffff0000, v47
	v_and_b32_e32 v47, 0xffff0000, v39
	v_pk_mul_f32 v[44:45], v[46:47], v[44:45]
	s_waitcnt vmcnt(2)
	v_lshlrev_b32_e32 v46, 16, v32
	v_cvt_pk_bf16_f32 v39, v44, v45
	global_store_dwordx4 v[40:41], v[36:39], off sc1
	s_nop 1
	v_add_u32_e32 v40, 8, v42
	v_lshl_add_u32 v36, v40, 7, v43
	ds_read_b128 v[36:39], v36
	v_and_b32_e32 v47, 0xffff0000, v32
	v_add_u32_e32 v40, s56, v40
	v_ashrrev_i32_e32 v41, 31, v40
	s_waitcnt lgkmcnt(0)
	v_lshlrev_b32_e32 v44, 16, v36
	v_and_b32_e32 v45, 0xffff0000, v36
	v_pk_mul_f32 v[44:45], v[46:47], v[44:45]
	v_lshlrev_b32_e32 v36, 16, v37
	v_cvt_pk_bf16_f32 v32, v44, v45
	v_and_b32_e32 v37, 0xffff0000, v37
	v_lshlrev_b32_e32 v44, 16, v33
	v_and_b32_e32 v45, 0xffff0000, v33
	v_pk_mul_f32 v[36:37], v[44:45], v[36:37]
	v_lshlrev_b32_e32 v44, 16, v34
	v_cvt_pk_bf16_f32 v33, v36, v37
	v_lshlrev_b32_e32 v36, 16, v38
	v_and_b32_e32 v37, 0xffff0000, v38
	v_and_b32_e32 v45, 0xffff0000, v34
	v_pk_mul_f32 v[36:37], v[44:45], v[36:37]
	v_lshlrev_b32_e32 v38, 16, v35
	v_cvt_pk_bf16_f32 v34, v36, v37
	v_lshlrev_b32_e32 v36, 16, v39
	v_and_b32_e32 v37, 0xffff0000, v39
	v_and_b32_e32 v39, 0xffff0000, v35
	v_pk_mul_f32 v[36:37], v[38:39], v[36:37]
	s_nop 0
	v_cvt_pk_bf16_f32 v35, v36, v37
	v_lshlrev_b64 v[36:37], 11, v[40:41]
	v_lshl_add_u64 v[36:37], s[30:31], 0, v[36:37]
	v_lshl_add_u64 v[36:37], v[36:37], 0, s[6:7]
	v_lshl_add_u64 v[36:37], v[36:37], 0, v[112:113]
	global_store_dwordx4 v[36:37], v[32:35], off sc1
	s_nop 1
	v_add_u32_e32 v36, 16, v42
	v_lshl_add_u32 v32, v36, 7, v43
	ds_read_b128 v[32:35], v32
	s_waitcnt vmcnt(3)
	v_lshlrev_b32_e32 v40, 16, v28
	v_and_b32_e32 v41, 0xffff0000, v28
	v_add_u32_e32 v36, s56, v36
	v_ashrrev_i32_e32 v37, 31, v36
	s_waitcnt lgkmcnt(0)
	v_lshlrev_b32_e32 v38, 16, v32
	v_and_b32_e32 v39, 0xffff0000, v32
	v_pk_mul_f32 v[38:39], v[40:41], v[38:39]
	v_lshlrev_b32_e32 v32, 16, v33
	v_cvt_pk_bf16_f32 v28, v38, v39
	v_and_b32_e32 v33, 0xffff0000, v33
	v_lshlrev_b32_e32 v38, 16, v29
	v_and_b32_e32 v39, 0xffff0000, v29
	v_pk_mul_f32 v[32:33], v[38:39], v[32:33]
	v_lshlrev_b32_e32 v38, 16, v30
	v_cvt_pk_bf16_f32 v29, v32, v33
	v_lshlrev_b32_e32 v32, 16, v34
	v_and_b32_e32 v33, 0xffff0000, v34
	v_and_b32_e32 v39, 0xffff0000, v30
	v_pk_mul_f32 v[32:33], v[38:39], v[32:33]
	v_lshlrev_b32_e32 v34, 16, v31
	v_cvt_pk_bf16_f32 v30, v32, v33
	v_lshlrev_b32_e32 v32, 16, v35
	v_and_b32_e32 v33, 0xffff0000, v35
	v_and_b32_e32 v35, 0xffff0000, v31
	v_pk_mul_f32 v[32:33], v[34:35], v[32:33]
	s_nop 0
	v_cvt_pk_bf16_f32 v31, v32, v33
	v_lshlrev_b64 v[32:33], 11, v[36:37]
	v_lshl_add_u64 v[32:33], s[30:31], 0, v[32:33]
	v_lshl_add_u64 v[32:33], v[32:33], 0, s[6:7]
	v_lshl_add_u64 v[32:33], v[32:33], 0, v[112:113]
	global_store_dwordx4 v[32:33], v[28:31], off sc1
	s_nop 1
	v_add_u32_e32 v32, 24, v42
	v_lshl_add_u32 v28, v32, 7, v43
	ds_read_b128 v[28:31], v28
	s_waitcnt vmcnt(3)
	v_lshlrev_b32_e32 v36, 16, v24
	v_and_b32_e32 v37, 0xffff0000, v24
	v_add_u32_e32 v32, s56, v32
	v_ashrrev_i32_e32 v33, 31, v32
	s_waitcnt lgkmcnt(0)
	v_lshlrev_b32_e32 v34, 16, v28
	v_and_b32_e32 v35, 0xffff0000, v28
	v_pk_mul_f32 v[34:35], v[36:37], v[34:35]
	v_lshlrev_b32_e32 v28, 16, v29
	v_cvt_pk_bf16_f32 v24, v34, v35
	v_and_b32_e32 v29, 0xffff0000, v29
	v_lshlrev_b32_e32 v34, 16, v25
	v_and_b32_e32 v35, 0xffff0000, v25
	v_pk_mul_f32 v[28:29], v[34:35], v[28:29]
	v_lshlrev_b32_e32 v34, 16, v26
	v_cvt_pk_bf16_f32 v25, v28, v29
	v_lshlrev_b32_e32 v28, 16, v30
	v_and_b32_e32 v29, 0xffff0000, v30
	v_and_b32_e32 v35, 0xffff0000, v26
	v_pk_mul_f32 v[28:29], v[34:35], v[28:29]
	v_lshlrev_b32_e32 v30, 16, v27
	v_cvt_pk_bf16_f32 v26, v28, v29
	v_lshlrev_b32_e32 v28, 16, v31
	v_and_b32_e32 v29, 0xffff0000, v31
	v_and_b32_e32 v31, 0xffff0000, v27
	v_pk_mul_f32 v[28:29], v[30:31], v[28:29]
	s_nop 0
	v_cvt_pk_bf16_f32 v27, v28, v29
	v_lshlrev_b64 v[28:29], 11, v[32:33]
	v_lshl_add_u64 v[28:29], s[30:31], 0, v[28:29]
	v_lshl_add_u64 v[28:29], v[28:29], 0, s[6:7]
	v_lshl_add_u64 v[28:29], v[28:29], 0, v[112:113]
	global_store_dwordx4 v[28:29], v[24:27], off sc1
	s_nop 1
	s_mov_b64 s[6:7], 0
	s_cbranch_vccnz .LBB0_1421
	s_waitcnt vmcnt(0) lgkmcnt(0)
	s_and_b64 s[34:35], s[4:5], exec

.LBB0_1503:
	s_movk_i32 s64, 0x2000
	v_cmp_gt_u32_e32 vcc, 32, v188
	s_and_saveexec_b64 s[2:3], vcc
	v_lshl_add_u32 v44, v188, 2, s97
	ds_write_b32 v44, v43 offset:128
	s_or_b64 exec, exec, s[2:3]
	s_waitcnt lgkmcnt(0)
	ds_read_b128 v[44:47], v172 offset:128
	v_mov_b32_e32 v48, v80
	v_mov_b32_e32 v49, v96
	v_lshlrev_b32_e32 v43, 1, v193
	v_mov_b32_e32 v96, v81
	s_waitcnt lgkmcnt(0)
	v_rcp_f32_e32 v44, v44
	s_waitcnt vmcnt(3)
	v_lshlrev_b32_e32 v50, 16, v36
	v_and_b32_e32 v51, 0xffff0000, v36
	v_lshl_add_u64 v[40:41], s[30:31], 0, v[40:41]
	v_pk_mul_f32 v[48:49], v[48:49], v[44:45] op_sel_hi:[1,0]
	v_lshl_add_u64 v[40:41], v[40:41], 0, s[4:5]
	v_cvt_pk_bf16_f32 v44, v48, v49
	v_lshlrev_b32_e32 v48, 9, v192
	v_add3_u32 v43, s74, v43, v48
	ds_write_b16 v43, v44
	ds_write_b16_d16_hi v43, v44 offset:64
	v_rcp_f32_e32 v44, v45
	v_mov_b32_e32 v48, v82
	v_mov_b32_e32 v49, v98
	v_mov_b32_e32 v98, v83
	v_pk_mul_f32 v[44:45], v[96:97], v[44:45] op_sel_hi:[1,0]
	v_lshl_add_u64 v[40:41], v[40:41], 0, v[112:113]
	v_cvt_pk_bf16_f32 v44, v44, v45
	ds_write_b16 v43, v44 offset:128
	ds_write_b16_d16_hi v43, v44 offset:192
	v_rcp_f32_e32 v44, v46
	s_andn2_b64 vcc, exec, s[60:61]
	v_pk_mul_f32 v[44:45], v[48:49], v[44:45] op_sel_hi:[1,0]
	s_nop 0
	v_cvt_pk_bf16_f32 v44, v44, v45
	ds_write_b16 v43, v44 offset:256
	ds_write_b16_d16_hi v43, v44 offset:320
	v_rcp_f32_e32 v44, v47
	v_mov_b32_e32 v48, v84
	v_mov_b32_e32 v49, v100
	v_mov_b32_e32 v100, v85
	v_pk_mul_f32 v[44:45], v[98:99], v[44:45] op_sel_hi:[1,0]
	s_nop 0
	v_cvt_pk_bf16_f32 v44, v44, v45
	ds_write_b16 v43, v44 offset:384
	ds_write_b16_d16_hi v43, v44 offset:448
	ds_read_b128 v[44:47], v172 offset:160
	s_waitcnt lgkmcnt(0)
	v_rcp_f32_e32 v44, v44
	s_nop 0
	v_pk_mul_f32 v[48:49], v[48:49], v[44:45] op_sel_hi:[1,0]
	s_nop 0
	v_cvt_pk_bf16_f32 v44, v48, v49
	ds_write_b16 v43, v44 offset:1024
	ds_write_b16_d16_hi v43, v44 offset:1088
	v_rcp_f32_e32 v44, v45
	v_mov_b32_e32 v48, v86
	v_mov_b32_e32 v49, v102
	v_mov_b32_e32 v102, v87
	v_pk_mul_f32 v[44:45], v[100:101], v[44:45] op_sel_hi:[1,0]
	s_nop 0
	v_cvt_pk_bf16_f32 v44, v44, v45
	ds_write_b16 v43, v44 offset:1152
	ds_write_b16_d16_hi v43, v44 offset:1216
	v_rcp_f32_e32 v44, v46
	s_nop 0
	v_pk_mul_f32 v[44:45], v[48:49], v[44:45] op_sel_hi:[1,0]
	s_nop 0
	v_cvt_pk_bf16_f32 v44, v44, v45
	ds_write_b16 v43, v44 offset:1280
	ds_write_b16_d16_hi v43, v44 offset:1344
	v_rcp_f32_e32 v44, v47
	v_mov_b32_e32 v48, v88
	v_mov_b32_e32 v49, v104
	v_mov_b32_e32 v104, v89
	v_pk_mul_f32 v[44:45], v[102:103], v[44:45] op_sel_hi:[1,0]
	s_nop 0
	v_cvt_pk_bf16_f32 v44, v44, v45
	ds_write_b16 v43, v44 offset:1408
	ds_write_b16_d16_hi v43, v44 offset:1472
	ds_read_b128 v[44:47], v172 offset:192
	s_waitcnt lgkmcnt(0)
	v_rcp_f32_e32 v44, v44
	s_nop 0
	v_pk_mul_f32 v[48:49], v[48:49], v[44:45] op_sel_hi:[1,0]
	s_nop 0
	v_cvt_pk_bf16_f32 v44, v48, v49
	ds_write_b16 v43, v44 offset:2048
	ds_write_b16_d16_hi v43, v44 offset:2112
	v_rcp_f32_e32 v44, v45
	v_mov_b32_e32 v48, v90
	v_mov_b32_e32 v49, v106
	v_mov_b32_e32 v106, v91
	v_pk_mul_f32 v[44:45], v[104:105], v[44:45] op_sel_hi:[1,0]
	s_nop 0
	v_cvt_pk_bf16_f32 v44, v44, v45
	ds_write_b16 v43, v44 offset:2176
	ds_write_b16_d16_hi v43, v44 offset:2240
	v_rcp_f32_e32 v44, v46
	s_nop 0
	v_pk_mul_f32 v[44:45], v[48:49], v[44:45] op_sel_hi:[1,0]
	s_nop 0
	v_cvt_pk_bf16_f32 v44, v44, v45
	ds_write_b16 v43, v44 offset:2304
	ds_write_b16_d16_hi v43, v44 offset:2368
	v_rcp_f32_e32 v44, v47
	v_mov_b32_e32 v48, v92
	v_mov_b32_e32 v49, v108
	v_mov_b32_e32 v108, v93
	v_pk_mul_f32 v[44:45], v[106:107], v[44:45] op_sel_hi:[1,0]
	s_nop 0
	v_cvt_pk_bf16_f32 v44, v44, v45
	ds_write_b16 v43, v44 offset:2432
	ds_write_b16_d16_hi v43, v44 offset:2496
	ds_read_b128 v[44:47], v172 offset:224
	s_waitcnt lgkmcnt(0)
	v_rcp_f32_e32 v44, v44
	s_nop 0
	v_pk_mul_f32 v[48:49], v[48:49], v[44:45] op_sel_hi:[1,0]
	s_nop 0
	v_cvt_pk_bf16_f32 v44, v48, v49
	ds_write_b16 v43, v44 offset:3072
	ds_write_b16_d16_hi v43, v44 offset:3136
	v_rcp_f32_e32 v44, v45
	v_mov_b32_e32 v48, v94
	v_mov_b32_e32 v49, v110
	v_mov_b32_e32 v110, v95
	v_pk_mul_f32 v[44:45], v[108:109], v[44:45] op_sel_hi:[1,0]
	s_nop 0
	v_cvt_pk_bf16_f32 v44, v44, v45
	ds_write_b16 v43, v44 offset:3200
	ds_write_b16_d16_hi v43, v44 offset:3264
	v_rcp_f32_e32 v44, v46
	s_nop 0
	v_pk_mul_f32 v[44:45], v[48:49], v[44:45] op_sel_hi:[1,0]
	s_nop 0
	v_cvt_pk_bf16_f32 v44, v44, v45
	ds_write_b16 v43, v44 offset:3328
	ds_write_b16_d16_hi v43, v44 offset:3392
	v_rcp_f32_e32 v44, v47
	s_nop 0
	v_pk_mul_f32 v[44:45], v[110:111], v[44:45] op_sel_hi:[1,0]
	s_nop 0
	v_cvt_pk_bf16_f32 v44, v44, v45
	ds_write_b16 v43, v44 offset:3456
	ds_write_b16_d16_hi v43, v44 offset:3520
	v_add_u32_e32 v43, s74, v112
	s_waitcnt lgkmcnt(0)
	v_lshl_add_u32 v44, v42, 7, v43
	ds_read_b128 v[44:47], v44
	s_waitcnt lgkmcnt(0)
	v_lshlrev_b32_e32 v48, 16, v44
	v_and_b32_e32 v49, 0xffff0000, v44
	v_pk_mul_f32 v[48:49], v[50:51], v[48:49]
	v_lshlrev_b32_e32 v44, 16, v45
	v_cvt_pk_bf16_f32 v36, v48, v49
	v_and_b32_e32 v45, 0xffff0000, v45
	v_lshlrev_b32_e32 v48, 16, v37
	v_and_b32_e32 v49, 0xffff0000, v37
	v_pk_mul_f32 v[44:45], v[48:49], v[44:45]
	v_lshlrev_b32_e32 v48, 16, v38
	v_cvt_pk_bf16_f32 v37, v44, v45
	v_lshlrev_b32_e32 v44, 16, v46
	v_and_b32_e32 v45, 0xffff0000, v46
	v_and_b32_e32 v49, 0xffff0000, v38
	v_pk_mul_f32 v[44:45], v[48:49], v[44:45]
	v_lshlrev_b32_e32 v46, 16, v39
	v_cvt_pk_bf16_f32 v38, v44, v45
	v_lshlrev_b32_e32 v44, 16, v47
	v_and_b32_e32 v45, 0xffff0000, v47
	v_and_b32_e32 v47, 0xffff0000, v39
	v_pk_mul_f32 v[44:45], v[46:47], v[44:45]
	s_waitcnt vmcnt(2)
	v_lshlrev_b32_e32 v46, 16, v32
	v_cvt_pk_bf16_f32 v39, v44, v45
	global_store_dwordx4 v[40:41], v[36:39], off sc1
	s_nop 1
	v_add_u32_e32 v40, 8, v42
	v_lshl_add_u32 v36, v40, 7, v43
	ds_read_b128 v[36:39], v36
	v_and_b32_e32 v47, 0xffff0000, v32
	v_add_u32_e32 v40, s56, v40
	v_ashrrev_i32_e32 v41, 31, v40
	s_waitcnt lgkmcnt(0)
	v_lshlrev_b32_e32 v44, 16, v36
	v_and_b32_e32 v45, 0xffff0000, v36
	v_pk_mul_f32 v[44:45], v[46:47], v[44:45]
	v_lshlrev_b32_e32 v36, 16, v37
	v_cvt_pk_bf16_f32 v32, v44, v45
	v_and_b32_e32 v37, 0xffff0000, v37
	v_lshlrev_b32_e32 v44, 16, v33
	v_and_b32_e32 v45, 0xffff0000, v33
	v_pk_mul_f32 v[36:37], v[44:45], v[36:37]
	v_lshlrev_b32_e32 v44, 16, v34
	v_cvt_pk_bf16_f32 v33, v36, v37
	v_lshlrev_b32_e32 v36, 16, v38
	v_and_b32_e32 v37, 0xffff0000, v38
	v_and_b32_e32 v45, 0xffff0000, v34
	v_pk_mul_f32 v[36:37], v[44:45], v[36:37]
	v_lshlrev_b32_e32 v38, 16, v35
	v_cvt_pk_bf16_f32 v34, v36, v37
	v_lshlrev_b32_e32 v36, 16, v39
	v_and_b32_e32 v37, 0xffff0000, v39
	v_and_b32_e32 v39, 0xffff0000, v35
	v_pk_mul_f32 v[36:37], v[38:39], v[36:37]
	s_nop 0
	v_cvt_pk_bf16_f32 v35, v36, v37
	v_lshlrev_b64 v[36:37], 11, v[40:41]
	v_lshl_add_u64 v[36:37], s[30:31], 0, v[36:37]
	v_lshl_add_u64 v[36:37], v[36:37], 0, s[4:5]
	v_lshl_add_u64 v[36:37], v[36:37], 0, v[112:113]
	global_store_dwordx4 v[36:37], v[32:35], off sc1
	s_nop 1
	v_add_u32_e32 v36, 16, v42
	v_lshl_add_u32 v32, v36, 7, v43
	ds_read_b128 v[32:35], v32
	s_waitcnt vmcnt(3)
	v_lshlrev_b32_e32 v40, 16, v28
	v_and_b32_e32 v41, 0xffff0000, v28
	v_add_u32_e32 v36, s56, v36
	v_ashrrev_i32_e32 v37, 31, v36
	s_waitcnt lgkmcnt(0)
	v_lshlrev_b32_e32 v38, 16, v32
	v_and_b32_e32 v39, 0xffff0000, v32
	v_pk_mul_f32 v[38:39], v[40:41], v[38:39]
	v_lshlrev_b32_e32 v32, 16, v33
	v_cvt_pk_bf16_f32 v28, v38, v39
	v_and_b32_e32 v33, 0xffff0000, v33
	v_lshlrev_b32_e32 v38, 16, v29
	v_and_b32_e32 v39, 0xffff0000, v29
	v_pk_mul_f32 v[32:33], v[38:39], v[32:33]
	v_lshlrev_b32_e32 v38, 16, v30
	v_cvt_pk_bf16_f32 v29, v32, v33
	v_lshlrev_b32_e32 v32, 16, v34
	v_and_b32_e32 v33, 0xffff0000, v34
	v_and_b32_e32 v39, 0xffff0000, v30
	v_pk_mul_f32 v[32:33], v[38:39], v[32:33]
	v_lshlrev_b32_e32 v34, 16, v31
	v_cvt_pk_bf16_f32 v30, v32, v33
	v_lshlrev_b32_e32 v32, 16, v35
	v_and_b32_e32 v33, 0xffff0000, v35
	v_and_b32_e32 v35, 0xffff0000, v31
	v_pk_mul_f32 v[32:33], v[34:35], v[32:33]
	s_nop 0
	v_cvt_pk_bf16_f32 v31, v32, v33
	v_lshlrev_b64 v[32:33], 11, v[36:37]
	v_lshl_add_u64 v[32:33], s[30:31], 0, v[32:33]
	v_lshl_add_u64 v[32:33], v[32:33], 0, s[4:5]
	v_lshl_add_u64 v[32:33], v[32:33], 0, v[112:113]
	global_store_dwordx4 v[32:33], v[28:31], off sc1
	s_nop 1
	v_add_u32_e32 v32, 24, v42
	v_lshl_add_u32 v28, v32, 7, v43
	ds_read_b128 v[28:31], v28
	s_waitcnt vmcnt(3)
	v_lshlrev_b32_e32 v36, 16, v24
	v_and_b32_e32 v37, 0xffff0000, v24
	v_add_u32_e32 v32, s56, v32
	v_ashrrev_i32_e32 v33, 31, v32
	s_waitcnt lgkmcnt(0)
	v_lshlrev_b32_e32 v34, 16, v28
	v_and_b32_e32 v35, 0xffff0000, v28
	v_pk_mul_f32 v[34:35], v[36:37], v[34:35]
	v_lshlrev_b32_e32 v28, 16, v29
	v_cvt_pk_bf16_f32 v24, v34, v35
	v_and_b32_e32 v29, 0xffff0000, v29
	v_lshlrev_b32_e32 v34, 16, v25
	v_and_b32_e32 v35, 0xffff0000, v25
	v_pk_mul_f32 v[28:29], v[34:35], v[28:29]
	v_lshlrev_b32_e32 v34, 16, v26
	v_cvt_pk_bf16_f32 v25, v28, v29
	v_lshlrev_b32_e32 v28, 16, v30
	v_and_b32_e32 v29, 0xffff0000, v30
	v_and_b32_e32 v35, 0xffff0000, v26
	v_pk_mul_f32 v[28:29], v[34:35], v[28:29]
	v_lshlrev_b32_e32 v30, 16, v27
	v_cvt_pk_bf16_f32 v26, v28, v29
	v_lshlrev_b32_e32 v28, 16, v31
	v_and_b32_e32 v29, 0xffff0000, v31
	v_and_b32_e32 v31, 0xffff0000, v27
	v_pk_mul_f32 v[28:29], v[30:31], v[28:29]
	s_nop 0
	v_cvt_pk_bf16_f32 v27, v28, v29
	v_lshlrev_b64 v[28:29], 11, v[32:33]
	v_lshl_add_u64 v[28:29], s[30:31], 0, v[28:29]
	v_lshl_add_u64 v[28:29], v[28:29], 0, s[4:5]
	v_lshl_add_u64 v[28:29], v[28:29], 0, v[112:113]
	global_store_dwordx4 v[28:29], v[24:27], off sc1
	s_nop 1
	s_cbranch_vccnz .LBB0_1507
	s_waitcnt vmcnt(0) lgkmcnt(0)
	s_andn2_b64 s[2:3], s[34:35], exec
	s_and_b64 s[4:5], s[10:11], exec
	s_or_b64 s[34:35], s[2:3], s[4:5]
